# GEMM unit head: 128 accumulator clears removed; first K-tile of each unit (up and in-projection GEMMs) runs a peeled copy whose first MFMA per accumulator takes C=0
# speedup vs baseline: 1.1091x; 1.0020x over previous
.LBB0_231:
	s_ashr_i32 s17, s16, 31
	s_lshl_b64 s[18:19], s[16:17], 19
	s_add_u32 s18, s28, s18
	s_addc_u32 s19, s29, s19
	s_and_b64 s[20:21], s[4:5], exec
	s_cselect_b32 s7, s19, s25
	s_cselect_b32 s17, s18, s24
	s_ashr_i32 s15, s14, 31
	s_lshl_b64 s[20:21], s[14:15], 19
	s_add_u32 s20, s30, s20
	s_addc_u32 s21, s31, s21
	s_and_b64 s[26:27], s[4:5], exec
	s_cselect_b32 s15, s21, s1
	s_cselect_b32 s41, s20, s0
	s_add_u32 s42, s0, 0x100
	s_addc_u32 s43, s1, 0
	s_add_u32 s0, s24, 0x40080
	v_mov_b32_e32 v4, 0
	s_addc_u32 s1, s25, 0
	s_mov_b32 s44, -2
	s_add_u32 s24, s0, 0xfffc0080
	s_addc_u32 s25, s1, -1
	s_add_i32 s45, 0, 0x10000
	s_cmp_eq_u32 s44, 12
	s_cselect_b32 s27, s7, s25
	s_cselect_b32 s26, s17, s24
	s_cselect_b32 s25, s15, s43
	s_cselect_b32 s24, s41, s42
	s_add_i32 s48, 0, 0x14000
	v_add_u32_e32 v154, s45, v151
	v_add_u32_e32 v166, s48, v151
	ds_read_b128 v[128:131], v154
	ds_read_b128 v[132:135], v154 offset:1024
	ds_read_b128 v[146:149], v154 offset:2048
	ds_read_b128 v[154:157], v154 offset:3072
	ds_read_b128 v[158:161], v166
	ds_read_b128 v[162:165], v166 offset:1024
	ds_read_b128 v[170:173], v166 offset:2048
	ds_read_b128 v[174:177], v166 offset:3072
	v_lshl_add_u64 v[166:167], s[0:1], 0, v[144:145]
	s_add_i32 m0, s23, 0xc000
	ds_read_b128 v[178:181], v153
	ds_read_b128 v[182:185], v153 offset:1024
	ds_read_b128 v[186:189], v153 offset:2048
	ds_read_b128 v[190:193], v153 offset:3072
	ds_read_b128 v[194:197], v153 offset:4096
	ds_read_b128 v[198:201], v153 offset:5120
	ds_read_b128 v[202:205], v153 offset:6144
	ds_read_b128 v[212:215], v153 offset:7168
	global_load_lds_dwordx4 v[166:167], off
	v_lshl_add_u64 v[166:167], s[0:1], 0, v[142:143]
	s_add_i32 m0, s23, 0xe000
	s_nop 0
	global_load_lds_dwordx4 v[166:167], off
	s_waitcnt vmcnt(8)
	s_waitcnt lgkmcnt(0)
	s_barrier
	s_waitcnt lgkmcnt(0)
	v_mfma_f32_16x16x32_bf16 v[120:123], v[128:131], v[178:181], 0
	v_mfma_f32_16x16x32_bf16 v[124:127], v[146:149], v[178:181], 0
	v_mfma_f32_16x16x32_bf16 v[104:107], v[128:131], v[186:189], 0
	v_mfma_f32_16x16x32_bf16 v[108:111], v[146:149], v[186:189], 0
	v_mfma_f32_16x16x32_bf16 v[88:91], v[128:131], v[194:197], 0
	v_mfma_f32_16x16x32_bf16 v[92:95], v[146:149], v[194:197], 0
	v_mfma_f32_16x16x32_bf16 v[72:75], v[128:131], v[202:205], 0
	v_mfma_f32_16x16x32_bf16 v[76:79], v[146:149], v[202:205], 0
	v_mfma_f32_16x16x32_bf16 v[120:123], v[132:135], v[182:185], v[120:123]
	v_mfma_f32_16x16x32_bf16 v[124:127], v[154:157], v[182:185], v[124:127]
	v_mfma_f32_16x16x32_bf16 v[104:107], v[132:135], v[190:193], v[104:107]
	v_mfma_f32_16x16x32_bf16 v[108:111], v[154:157], v[190:193], v[108:111]
	v_mfma_f32_16x16x32_bf16 v[88:91], v[132:135], v[198:201], v[88:91]
	v_mfma_f32_16x16x32_bf16 v[92:95], v[154:157], v[198:201], v[92:95]
	v_mfma_f32_16x16x32_bf16 v[72:75], v[132:135], v[212:215], v[72:75]
	v_mfma_f32_16x16x32_bf16 v[76:79], v[154:157], v[212:215], v[76:79]
	v_mfma_f32_16x16x32_bf16 v[112:115], v[158:161], v[178:181], 0
	v_mfma_f32_16x16x32_bf16 v[116:119], v[170:173], v[178:181], 0
	v_mfma_f32_16x16x32_bf16 v[96:99], v[158:161], v[186:189], 0
	v_mfma_f32_16x16x32_bf16 v[100:103], v[170:173], v[186:189], 0
	v_mfma_f32_16x16x32_bf16 v[80:83], v[158:161], v[194:197], 0
	v_mfma_f32_16x16x32_bf16 v[84:87], v[170:173], v[194:197], 0
	v_mfma_f32_16x16x32_bf16 v[64:67], v[158:161], v[202:205], 0
	v_mfma_f32_16x16x32_bf16 v[68:71], v[170:173], v[202:205], 0
	v_mfma_f32_16x16x32_bf16 v[112:115], v[162:165], v[182:185], v[112:115]
	v_mfma_f32_16x16x32_bf16 v[116:119], v[174:177], v[182:185], v[116:119]
	v_mfma_f32_16x16x32_bf16 v[96:99], v[162:165], v[190:193], v[96:99]
	v_mfma_f32_16x16x32_bf16 v[100:103], v[174:177], v[190:193], v[100:103]
	v_mfma_f32_16x16x32_bf16 v[80:83], v[162:165], v[198:201], v[80:83]
	v_mfma_f32_16x16x32_bf16 v[84:87], v[174:177], v[198:201], v[84:87]
	v_mfma_f32_16x16x32_bf16 v[64:67], v[162:165], v[212:215], v[64:67]
	v_mfma_f32_16x16x32_bf16 v[68:71], v[174:177], v[212:215], v[68:71]
	s_barrier
	s_add_i32 s45, s45, s34
	v_lshl_add_u64 v[166:167], s[24:25], 0, v[168:169]
	s_mov_b32 m0, s45
	ds_read_b128 v[178:181], v153 offset:16384
	ds_read_b128 v[182:185], v153 offset:17408
	ds_read_b128 v[186:189], v153 offset:18432
	ds_read_b128 v[190:193], v153 offset:19456
	ds_read_b128 v[194:197], v153 offset:20480
	ds_read_b128 v[198:201], v153 offset:21504
	ds_read_b128 v[202:205], v153 offset:22528
	ds_read_b128 v[212:215], v153 offset:23552
	global_load_lds_dwordx4 v[166:167], off
	s_add_i32 m0, s45, 0x2000
	s_add_u32 s46, s24, 0x40000
	v_lshl_add_u64 v[216:217], s[24:25], 0, v[140:141]
	s_addc_u32 s47, s25, 0
	s_add_i32 s45, s48, s34
	global_load_lds_dwordx4 v[216:217], off
	v_lshl_add_u64 v[218:219], s[46:47], 0, v[168:169]
	s_mov_b32 m0, s45
	v_lshl_add_u64 v[220:221], s[26:27], 0, v[138:139]
	global_load_lds_dwordx4 v[218:219], off
	v_lshl_add_u64 v[218:219], s[46:47], 0, v[140:141]
	s_add_i32 m0, s45, 0x2000
	s_nop 0
	global_load_lds_dwordx4 v[218:219], off
	v_lshl_add_u64 v[218:219], s[26:27], 0, v[136:137]
	s_mov_b32 m0, s23
	s_nop 0
	global_load_lds_dwordx4 v[218:219], off
	s_mov_b32 m0, s35
	s_nop 0
	global_load_lds_dwordx4 v[220:221], off
	s_waitcnt vmcnt(8)
	s_waitcnt lgkmcnt(0)
	s_barrier
	s_waitcnt lgkmcnt(0)
	v_mfma_f32_16x16x32_bf16 v[56:59], v[128:131], v[178:181], 0
	v_mfma_f32_16x16x32_bf16 v[60:63], v[146:149], v[178:181], 0
	v_mfma_f32_16x16x32_bf16 v[40:43], v[128:131], v[186:189], 0
	v_mfma_f32_16x16x32_bf16 v[44:47], v[146:149], v[186:189], 0
	v_mfma_f32_16x16x32_bf16 v[24:27], v[128:131], v[194:197], 0
	v_mfma_f32_16x16x32_bf16 v[28:31], v[146:149], v[194:197], 0
	v_mfma_f32_16x16x32_bf16 v[8:11], v[128:131], v[202:205], 0
	v_mfma_f32_16x16x32_bf16 v[12:15], v[146:149], v[202:205], 0
	v_mfma_f32_16x16x32_bf16 v[56:59], v[132:135], v[182:185], v[56:59]
	v_mfma_f32_16x16x32_bf16 v[60:63], v[154:157], v[182:185], v[60:63]
	v_mfma_f32_16x16x32_bf16 v[40:43], v[132:135], v[190:193], v[40:43]
	v_mfma_f32_16x16x32_bf16 v[44:47], v[154:157], v[190:193], v[44:47]
	v_mfma_f32_16x16x32_bf16 v[24:27], v[132:135], v[198:201], v[24:27]
	v_mfma_f32_16x16x32_bf16 v[28:31], v[154:157], v[198:201], v[28:31]
	v_mfma_f32_16x16x32_bf16 v[8:11], v[132:135], v[212:215], v[8:11]
	v_mfma_f32_16x16x32_bf16 v[12:15], v[154:157], v[212:215], v[12:15]
	v_mfma_f32_16x16x32_bf16 v[48:51], v[158:161], v[178:181], 0
	v_mfma_f32_16x16x32_bf16 v[52:55], v[170:173], v[178:181], 0
	v_mfma_f32_16x16x32_bf16 v[32:35], v[158:161], v[186:189], 0
	v_mfma_f32_16x16x32_bf16 v[36:39], v[170:173], v[186:189], 0
	v_mfma_f32_16x16x32_bf16 v[16:19], v[158:161], v[194:197], 0
	v_mfma_f32_16x16x32_bf16 v[20:23], v[170:173], v[194:197], 0
	v_mfma_f32_16x16x32_bf16 v[0:3], v[158:161], v[202:205], 0
	v_mfma_f32_16x16x32_bf16 v[4:7], v[170:173], v[202:205], 0
	v_mfma_f32_16x16x32_bf16 v[48:51], v[162:165], v[182:185], v[48:51]
	v_mfma_f32_16x16x32_bf16 v[52:55], v[174:177], v[182:185], v[52:55]
	v_mfma_f32_16x16x32_bf16 v[32:35], v[162:165], v[190:193], v[32:35]
	v_mfma_f32_16x16x32_bf16 v[36:39], v[174:177], v[190:193], v[36:39]
	v_mfma_f32_16x16x32_bf16 v[16:19], v[162:165], v[198:201], v[16:19]
	v_mfma_f32_16x16x32_bf16 v[20:23], v[174:177], v[198:201], v[20:23]
	v_mfma_f32_16x16x32_bf16 v[0:3], v[162:165], v[212:215], v[0:3]
	v_mfma_f32_16x16x32_bf16 v[4:7], v[174:177], v[212:215], v[4:7]
	s_barrier
	s_branch .Lpeel_p2

.Lpeel_p2:
	s_add_i32 s45, 0, 0x18000
	s_add_i32 s46, 0, 0x1c000
	v_add_u32_e32 v154, s45, v151
	v_add_u32_e32 v174, s46, v151
	ds_read_b128 v[128:131], v154
	ds_read_b128 v[132:135], v154 offset:1024
	ds_read_b128 v[146:149], v154 offset:2048
	ds_read_b128 v[154:157], v154 offset:3072
	ds_read_b128 v[158:161], v174
	ds_read_b128 v[162:165], v174 offset:1024
	ds_read_b128 v[170:173], v174 offset:2048
	ds_read_b128 v[174:177], v174 offset:3072
	s_add_u32 s26, s26, 0x40000
	s_addc_u32 s27, s27, 0
	s_mov_b32 m0, s36
	v_lshl_add_u64 v[222:223], s[26:27], 0, v[136:137]
	ds_read_b128 v[178:181], v153 offset:32768
	ds_read_b128 v[182:185], v153 offset:33792
	ds_read_b128 v[186:189], v153 offset:34816
	ds_read_b128 v[190:193], v153 offset:35840
	ds_read_b128 v[194:197], v153 offset:36864
	ds_read_b128 v[198:201], v153 offset:37888
	ds_read_b128 v[202:205], v153 offset:38912
	ds_read_b128 v[212:215], v153 offset:39936
	global_load_lds_dwordx4 v[222:223], off
	v_lshl_add_u64 v[222:223], s[26:27], 0, v[138:139]
	s_mov_b32 m0, s37
	s_nop 0
	global_load_lds_dwordx4 v[222:223], off
	s_waitcnt vmcnt(8)
	s_waitcnt lgkmcnt(0)
	s_barrier
	s_waitcnt lgkmcnt(0)
	v_mfma_f32_16x16x32_bf16 v[120:123], v[128:131], v[178:181], v[120:123]
	v_mfma_f32_16x16x32_bf16 v[124:127], v[146:149], v[178:181], v[124:127]
	v_mfma_f32_16x16x32_bf16 v[104:107], v[128:131], v[186:189], v[104:107]
	v_mfma_f32_16x16x32_bf16 v[108:111], v[146:149], v[186:189], v[108:111]
	v_mfma_f32_16x16x32_bf16 v[88:91], v[128:131], v[194:197], v[88:91]
	v_mfma_f32_16x16x32_bf16 v[92:95], v[146:149], v[194:197], v[92:95]
	v_mfma_f32_16x16x32_bf16 v[72:75], v[128:131], v[202:205], v[72:75]
	v_mfma_f32_16x16x32_bf16 v[76:79], v[146:149], v[202:205], v[76:79]
	v_mfma_f32_16x16x32_bf16 v[120:123], v[132:135], v[182:185], v[120:123]
	v_mfma_f32_16x16x32_bf16 v[124:127], v[154:157], v[182:185], v[124:127]
	v_mfma_f32_16x16x32_bf16 v[104:107], v[132:135], v[190:193], v[104:107]
	v_mfma_f32_16x16x32_bf16 v[108:111], v[154:157], v[190:193], v[108:111]
	v_mfma_f32_16x16x32_bf16 v[88:91], v[132:135], v[198:201], v[88:91]
	v_mfma_f32_16x16x32_bf16 v[92:95], v[154:157], v[198:201], v[92:95]
	v_mfma_f32_16x16x32_bf16 v[72:75], v[132:135], v[212:215], v[72:75]
	v_mfma_f32_16x16x32_bf16 v[76:79], v[154:157], v[212:215], v[76:79]
	v_mfma_f32_16x16x32_bf16 v[112:115], v[158:161], v[178:181], v[112:115]
	v_mfma_f32_16x16x32_bf16 v[116:119], v[170:173], v[178:181], v[116:119]
	v_mfma_f32_16x16x32_bf16 v[96:99], v[158:161], v[186:189], v[96:99]
	v_mfma_f32_16x16x32_bf16 v[100:103], v[170:173], v[186:189], v[100:103]
	v_mfma_f32_16x16x32_bf16 v[80:83], v[158:161], v[194:197], v[80:83]
	v_mfma_f32_16x16x32_bf16 v[84:87], v[170:173], v[194:197], v[84:87]
	v_mfma_f32_16x16x32_bf16 v[64:67], v[158:161], v[202:205], v[64:67]
	v_mfma_f32_16x16x32_bf16 v[68:71], v[170:173], v[202:205], v[68:71]
	v_mfma_f32_16x16x32_bf16 v[112:115], v[162:165], v[182:185], v[112:115]
	v_mfma_f32_16x16x32_bf16 v[116:119], v[174:177], v[182:185], v[116:119]
	v_mfma_f32_16x16x32_bf16 v[96:99], v[162:165], v[190:193], v[96:99]
	v_mfma_f32_16x16x32_bf16 v[100:103], v[174:177], v[190:193], v[100:103]
	v_mfma_f32_16x16x32_bf16 v[80:83], v[162:165], v[198:201], v[80:83]
	v_mfma_f32_16x16x32_bf16 v[84:87], v[174:177], v[198:201], v[84:87]
	v_mfma_f32_16x16x32_bf16 v[64:67], v[162:165], v[212:215], v[64:67]
	v_mfma_f32_16x16x32_bf16 v[68:71], v[174:177], v[212:215], v[68:71]
	s_barrier
	s_add_i32 s26, s45, s34
	v_lshl_add_u64 v[166:167], v[166:167], 0, s[74:75]
	s_mov_b32 m0, s26
	ds_read_b128 v[178:181], v153 offset:49152
	ds_read_b128 v[182:185], v153 offset:50176
	ds_read_b128 v[186:189], v153 offset:51200
	ds_read_b128 v[190:193], v153 offset:52224
	ds_read_b128 v[194:197], v153 offset:53248
	ds_read_b128 v[198:201], v153 offset:54272
	ds_read_b128 v[202:205], v153 offset:55296
	ds_read_b128 v[212:215], v153 offset:56320
	global_load_lds_dwordx4 v[166:167], off
	s_add_i32 m0, s26, 0x2000
	s_add_u32 s24, s24, 0x40080
	v_lshl_add_u64 v[166:167], v[216:217], 0, s[74:75]
	s_addc_u32 s25, s25, 0
	s_add_i32 s26, s46, s34
	global_load_lds_dwordx4 v[166:167], off
	v_lshl_add_u64 v[166:167], s[24:25], 0, v[168:169]
	s_mov_b32 m0, s26
	s_nop 0
	global_load_lds_dwordx4 v[166:167], off
	v_lshl_add_u64 v[166:167], s[24:25], 0, v[140:141]
	s_add_i32 m0, s26, 0x2000
	s_nop 0
	global_load_lds_dwordx4 v[166:167], off
	v_lshl_add_u64 v[166:167], v[218:219], 0, s[74:75]
	s_mov_b32 m0, s38
	s_nop 0
	global_load_lds_dwordx4 v[166:167], off
	v_lshl_add_u64 v[166:167], v[220:221], 0, s[74:75]
	s_mov_b32 m0, s39
	s_nop 0
	global_load_lds_dwordx4 v[166:167], off
	s_waitcnt vmcnt(8)
	s_waitcnt lgkmcnt(0)
	s_barrier
	s_waitcnt lgkmcnt(0)
	v_mfma_f32_16x16x32_bf16 v[56:59], v[128:131], v[178:181], v[56:59]
	v_mfma_f32_16x16x32_bf16 v[60:63], v[146:149], v[178:181], v[60:63]
	v_mfma_f32_16x16x32_bf16 v[40:43], v[128:131], v[186:189], v[40:43]
	v_mfma_f32_16x16x32_bf16 v[44:47], v[146:149], v[186:189], v[44:47]
	v_mfma_f32_16x16x32_bf16 v[24:27], v[128:131], v[194:197], v[24:27]
	v_mfma_f32_16x16x32_bf16 v[28:31], v[146:149], v[194:197], v[28:31]
	v_mfma_f32_16x16x32_bf16 v[8:11], v[128:131], v[202:205], v[8:11]
	v_mfma_f32_16x16x32_bf16 v[12:15], v[146:149], v[202:205], v[12:15]
	v_mfma_f32_16x16x32_bf16 v[56:59], v[132:135], v[182:185], v[56:59]
	v_mfma_f32_16x16x32_bf16 v[60:63], v[154:157], v[182:185], v[60:63]
	v_mfma_f32_16x16x32_bf16 v[40:43], v[132:135], v[190:193], v[40:43]
	v_mfma_f32_16x16x32_bf16 v[44:47], v[154:157], v[190:193], v[44:47]
	v_mfma_f32_16x16x32_bf16 v[24:27], v[132:135], v[198:201], v[24:27]
	v_mfma_f32_16x16x32_bf16 v[28:31], v[154:157], v[198:201], v[28:31]
	v_mfma_f32_16x16x32_bf16 v[8:11], v[132:135], v[212:215], v[8:11]
	v_mfma_f32_16x16x32_bf16 v[12:15], v[154:157], v[212:215], v[12:15]
	v_mfma_f32_16x16x32_bf16 v[48:51], v[158:161], v[178:181], v[48:51]
	v_mfma_f32_16x16x32_bf16 v[52:55], v[170:173], v[178:181], v[52:55]
	v_mfma_f32_16x16x32_bf16 v[32:35], v[158:161], v[186:189], v[32:35]
	v_mfma_f32_16x16x32_bf16 v[36:39], v[170:173], v[186:189], v[36:39]
	v_mfma_f32_16x16x32_bf16 v[16:19], v[158:161], v[194:197], v[16:19]
	v_mfma_f32_16x16x32_bf16 v[20:23], v[170:173], v[194:197], v[20:23]
	v_mfma_f32_16x16x32_bf16 v[0:3], v[158:161], v[202:205], v[0:3]
	v_mfma_f32_16x16x32_bf16 v[4:7], v[170:173], v[202:205], v[4:7]
	v_mfma_f32_16x16x32_bf16 v[48:51], v[162:165], v[182:185], v[48:51]
	v_mfma_f32_16x16x32_bf16 v[52:55], v[174:177], v[182:185], v[52:55]
	v_mfma_f32_16x16x32_bf16 v[32:35], v[162:165], v[190:193], v[32:35]
	v_mfma_f32_16x16x32_bf16 v[36:39], v[174:177], v[190:193], v[36:39]
	v_mfma_f32_16x16x32_bf16 v[16:19], v[162:165], v[198:201], v[16:19]
	v_mfma_f32_16x16x32_bf16 v[20:23], v[174:177], v[198:201], v[20:23]
	v_mfma_f32_16x16x32_bf16 v[0:3], v[162:165], v[212:215], v[0:3]
	v_mfma_f32_16x16x32_bf16 v[4:7], v[174:177], v[212:215], v[4:7]
	s_barrier
	s_add_i32 s44, s44, 2
	s_add_u32 s42, s42, 0x100
	s_addc_u32 s43, s43, 0
	s_add_u32 s0, s0, 0x100
	s_addc_u32 s1, s1, 0
	s_cmp_gt_u32 s44, 13
	s_cbranch_scc0 .LBB0_232
	s_and_b64 vcc, exec, s[12:13]
	s_cbranch_vccz .LBB0_235
	s_barrier

.LBB0_778:
	s_ashr_i32 s19, s18, 31
	s_lshl_b64 s[20:21], s[18:19], 19
	s_add_u32 s20, s30, s20
	s_addc_u32 s21, s31, s21
	s_and_b64 s[22:23], s[6:7], exec
	s_cselect_b32 s19, s21, s27
	s_cselect_b32 s46, s20, s26
	s_ashr_i32 s17, s16, 31
	s_lshl_b64 s[22:23], s[16:17], 19
	s_add_u32 s22, s34, s22
	s_addc_u32 s23, s35, s23
	s_and_b64 s[28:29], s[6:7], exec
	s_cselect_b32 s17, s23, s25
	s_cselect_b32 s47, s22, s24
	s_add_u32 s48, s24, 0x100
	s_addc_u32 s49, s25, 0
	s_add_u32 s24, s26, 0x40080
	v_mov_b32_e32 v0, 0
	s_addc_u32 s25, s27, 0
	s_mov_b32 s50, -2
	s_add_u32 s26, s24, 0xfffc0080
	s_addc_u32 s27, s25, -1
	s_add_i32 s51, 0, 0x10000
	s_cmp_eq_u32 s50, 12
	s_cselect_b32 s29, s19, s27
	s_cselect_b32 s28, s46, s26
	s_cselect_b32 s27, s17, s49
	s_cselect_b32 s26, s47, s48
	s_add_i32 s54, 0, 0x14000
	v_add_u32_e32 v140, s51, v191
	v_add_u32_e32 v156, s54, v191
	ds_read_b128 v[116:119], v140
	ds_read_b128 v[120:123], v140 offset:1024
	ds_read_b128 v[124:127], v140 offset:2048
	ds_read_b128 v[140:143], v140 offset:3072
	ds_read_b128 v[144:147], v156
	ds_read_b128 v[148:151], v156 offset:1024
	ds_read_b128 v[152:155], v156 offset:2048
	ds_read_b128 v[156:159], v156 offset:3072
	v_lshl_add_u64 v[188:189], s[24:25], 0, v[174:175]
	s_add_i32 m0, s37, 0xc000
	ds_read_b128 v[170:173], v193
	ds_read_b128 v[176:179], v193 offset:1024
	ds_read_b128 v[180:183], v193 offset:2048
	ds_read_b128 v[184:187], v193 offset:3072
	ds_read_b128 v[194:197], v193 offset:4096
	ds_read_b128 v[198:201], v193 offset:5120
	ds_read_b128 v[202:205], v193 offset:6144
	ds_read_b128 v[212:215], v193 offset:7168
	global_load_lds_dwordx4 v[188:189], off
	v_lshl_add_u64 v[188:189], s[24:25], 0, v[166:167]
	s_add_i32 m0, s37, 0xe000
	s_nop 0
	global_load_lds_dwordx4 v[188:189], off
	s_waitcnt vmcnt(8)
	s_waitcnt lgkmcnt(0)
	s_barrier
	s_waitcnt lgkmcnt(0)
	v_mfma_f32_16x16x32_bf16 v[136:139], v[116:119], v[170:173], 0
	v_mfma_f32_16x16x32_bf16 v[92:95], v[124:127], v[170:173], 0
	v_mfma_f32_16x16x32_bf16 v[132:135], v[116:119], v[180:183], 0
	v_mfma_f32_16x16x32_bf16 v[88:91], v[124:127], v[180:183], 0
	v_mfma_f32_16x16x32_bf16 v[112:115], v[116:119], v[194:197], 0
	v_mfma_f32_16x16x32_bf16 v[80:83], v[124:127], v[194:197], 0
	v_mfma_f32_16x16x32_bf16 v[104:107], v[116:119], v[202:205], 0
	v_mfma_f32_16x16x32_bf16 v[72:75], v[124:127], v[202:205], 0
	v_mfma_f32_16x16x32_bf16 v[136:139], v[120:123], v[176:179], v[136:139]
	v_mfma_f32_16x16x32_bf16 v[92:95], v[140:143], v[176:179], v[92:95]
	v_mfma_f32_16x16x32_bf16 v[132:135], v[120:123], v[184:187], v[132:135]
	v_mfma_f32_16x16x32_bf16 v[88:91], v[140:143], v[184:187], v[88:91]
	v_mfma_f32_16x16x32_bf16 v[112:115], v[120:123], v[198:201], v[112:115]
	v_mfma_f32_16x16x32_bf16 v[80:83], v[140:143], v[198:201], v[80:83]
	v_mfma_f32_16x16x32_bf16 v[104:107], v[120:123], v[212:215], v[104:107]
	v_mfma_f32_16x16x32_bf16 v[72:75], v[140:143], v[212:215], v[72:75]
	v_mfma_f32_16x16x32_bf16 v[128:131], v[144:147], v[170:173], 0
	v_mfma_f32_16x16x32_bf16 v[84:87], v[152:155], v[170:173], 0
	v_mfma_f32_16x16x32_bf16 v[108:111], v[144:147], v[180:183], 0
	v_mfma_f32_16x16x32_bf16 v[76:79], v[152:155], v[180:183], 0
	v_mfma_f32_16x16x32_bf16 v[100:103], v[144:147], v[194:197], 0
	v_mfma_f32_16x16x32_bf16 v[68:71], v[152:155], v[194:197], 0
	v_mfma_f32_16x16x32_bf16 v[96:99], v[144:147], v[202:205], 0
	v_mfma_f32_16x16x32_bf16 v[64:67], v[152:155], v[202:205], 0
	v_mfma_f32_16x16x32_bf16 v[128:131], v[148:151], v[176:179], v[128:131]
	v_mfma_f32_16x16x32_bf16 v[84:87], v[156:159], v[176:179], v[84:87]
	v_mfma_f32_16x16x32_bf16 v[108:111], v[148:151], v[184:187], v[108:111]
	v_mfma_f32_16x16x32_bf16 v[76:79], v[156:159], v[184:187], v[76:79]
	v_mfma_f32_16x16x32_bf16 v[100:103], v[148:151], v[198:201], v[100:103]
	v_mfma_f32_16x16x32_bf16 v[68:71], v[156:159], v[198:201], v[68:71]
	v_mfma_f32_16x16x32_bf16 v[96:99], v[148:151], v[212:215], v[96:99]
	v_mfma_f32_16x16x32_bf16 v[64:67], v[156:159], v[212:215], v[64:67]
	s_barrier
	s_add_i32 s51, s51, s36
	v_lshl_add_u64 v[188:189], s[26:27], 0, v[168:169]
	s_mov_b32 m0, s51
	ds_read_b128 v[170:173], v193 offset:16384
	ds_read_b128 v[176:179], v193 offset:17408
	ds_read_b128 v[180:183], v193 offset:18432
	ds_read_b128 v[184:187], v193 offset:19456
	ds_read_b128 v[194:197], v193 offset:20480
	ds_read_b128 v[198:201], v193 offset:21504
	ds_read_b128 v[202:205], v193 offset:22528
	ds_read_b128 v[212:215], v193 offset:23552
	global_load_lds_dwordx4 v[188:189], off
	s_add_i32 m0, s51, 0x2000
	s_add_u32 s52, s26, 0x40000
	v_lshl_add_u64 v[216:217], s[26:27], 0, v[160:161]
	s_addc_u32 s53, s27, 0
	s_add_i32 s51, s54, s36
	global_load_lds_dwordx4 v[216:217], off
	v_lshl_add_u64 v[218:219], s[52:53], 0, v[168:169]
	s_mov_b32 m0, s51
	v_lshl_add_u64 v[220:221], s[28:29], 0, v[162:163]
	global_load_lds_dwordx4 v[218:219], off
	v_lshl_add_u64 v[218:219], s[52:53], 0, v[160:161]
	s_add_i32 m0, s51, 0x2000
	s_nop 0
	global_load_lds_dwordx4 v[218:219], off
	v_lshl_add_u64 v[218:219], s[28:29], 0, v[164:165]
	s_mov_b32 m0, s37
	s_nop 0
	global_load_lds_dwordx4 v[218:219], off
	s_mov_b32 m0, s38
	s_nop 0
	global_load_lds_dwordx4 v[220:221], off
	s_waitcnt vmcnt(8)
	s_waitcnt lgkmcnt(0)
	s_barrier
	s_waitcnt lgkmcnt(0)
	v_mfma_f32_16x16x32_bf16 v[60:63], v[116:119], v[170:173], 0
	v_mfma_f32_16x16x32_bf16 v[28:31], v[124:127], v[170:173], 0
	v_mfma_f32_16x16x32_bf16 v[56:59], v[116:119], v[180:183], 0
	v_mfma_f32_16x16x32_bf16 v[24:27], v[124:127], v[180:183], 0
	v_mfma_f32_16x16x32_bf16 v[48:51], v[116:119], v[194:197], 0
	v_mfma_f32_16x16x32_bf16 v[16:19], v[124:127], v[194:197], 0
	v_mfma_f32_16x16x32_bf16 v[40:43], v[116:119], v[202:205], 0
	v_mfma_f32_16x16x32_bf16 v[8:11], v[124:127], v[202:205], 0
	v_mfma_f32_16x16x32_bf16 v[60:63], v[120:123], v[176:179], v[60:63]
	v_mfma_f32_16x16x32_bf16 v[28:31], v[140:143], v[176:179], v[28:31]
	v_mfma_f32_16x16x32_bf16 v[56:59], v[120:123], v[184:187], v[56:59]
	v_mfma_f32_16x16x32_bf16 v[24:27], v[140:143], v[184:187], v[24:27]
	v_mfma_f32_16x16x32_bf16 v[48:51], v[120:123], v[198:201], v[48:51]
	v_mfma_f32_16x16x32_bf16 v[16:19], v[140:143], v[198:201], v[16:19]
	v_mfma_f32_16x16x32_bf16 v[40:43], v[120:123], v[212:215], v[40:43]
	v_mfma_f32_16x16x32_bf16 v[8:11], v[140:143], v[212:215], v[8:11]
	v_mfma_f32_16x16x32_bf16 v[52:55], v[144:147], v[170:173], 0
	v_mfma_f32_16x16x32_bf16 v[20:23], v[152:155], v[170:173], 0
	v_mfma_f32_16x16x32_bf16 v[44:47], v[144:147], v[180:183], 0
	v_mfma_f32_16x16x32_bf16 v[12:15], v[152:155], v[180:183], 0
	v_mfma_f32_16x16x32_bf16 v[36:39], v[144:147], v[194:197], 0
	v_mfma_f32_16x16x32_bf16 v[4:7], v[152:155], v[194:197], 0
	v_mfma_f32_16x16x32_bf16 v[32:35], v[144:147], v[202:205], 0
	v_mfma_f32_16x16x32_bf16 v[0:3], v[152:155], v[202:205], 0
	v_mfma_f32_16x16x32_bf16 v[52:55], v[148:151], v[176:179], v[52:55]
	v_mfma_f32_16x16x32_bf16 v[20:23], v[156:159], v[176:179], v[20:23]
	v_mfma_f32_16x16x32_bf16 v[44:47], v[148:151], v[184:187], v[44:47]
	v_mfma_f32_16x16x32_bf16 v[12:15], v[156:159], v[184:187], v[12:15]
	v_mfma_f32_16x16x32_bf16 v[36:39], v[148:151], v[198:201], v[36:39]
	v_mfma_f32_16x16x32_bf16 v[4:7], v[156:159], v[198:201], v[4:7]
	v_mfma_f32_16x16x32_bf16 v[32:35], v[148:151], v[212:215], v[32:35]
	v_mfma_f32_16x16x32_bf16 v[0:3], v[156:159], v[212:215], v[0:3]
	s_barrier
	s_branch .Lpeel_p8

.Lpeel_p8:
	s_add_i32 s51, 0, 0x18000
	s_add_i32 s52, 0, 0x1c000
	v_add_u32_e32 v140, s51, v191
	v_add_u32_e32 v156, s52, v191
	ds_read_b128 v[116:119], v140
	ds_read_b128 v[120:123], v140 offset:1024
	ds_read_b128 v[124:127], v140 offset:2048
	ds_read_b128 v[140:143], v140 offset:3072
	ds_read_b128 v[144:147], v156
	ds_read_b128 v[148:151], v156 offset:1024
	ds_read_b128 v[152:155], v156 offset:2048
	ds_read_b128 v[156:159], v156 offset:3072
	s_add_u32 s28, s28, 0x40000
	s_addc_u32 s29, s29, 0
	s_mov_b32 m0, s39
	v_lshl_add_u64 v[222:223], s[28:29], 0, v[164:165]
	ds_read_b128 v[170:173], v193 offset:32768
	ds_read_b128 v[176:179], v193 offset:33792
	ds_read_b128 v[180:183], v193 offset:34816
	ds_read_b128 v[184:187], v193 offset:35840
	ds_read_b128 v[194:197], v193 offset:36864
	ds_read_b128 v[198:201], v193 offset:37888
	ds_read_b128 v[202:205], v193 offset:38912
	ds_read_b128 v[212:215], v193 offset:39936
	global_load_lds_dwordx4 v[222:223], off
	v_lshl_add_u64 v[222:223], s[28:29], 0, v[162:163]
	s_mov_b32 m0, s40
	s_nop 0
	global_load_lds_dwordx4 v[222:223], off
	s_waitcnt vmcnt(8)
	s_waitcnt lgkmcnt(0)
	s_barrier
	s_waitcnt lgkmcnt(0)
	v_mfma_f32_16x16x32_bf16 v[136:139], v[116:119], v[170:173], v[136:139]
	v_mfma_f32_16x16x32_bf16 v[92:95], v[124:127], v[170:173], v[92:95]
	v_mfma_f32_16x16x32_bf16 v[132:135], v[116:119], v[180:183], v[132:135]
	v_mfma_f32_16x16x32_bf16 v[88:91], v[124:127], v[180:183], v[88:91]
	v_mfma_f32_16x16x32_bf16 v[112:115], v[116:119], v[194:197], v[112:115]
	v_mfma_f32_16x16x32_bf16 v[80:83], v[124:127], v[194:197], v[80:83]
	v_mfma_f32_16x16x32_bf16 v[104:107], v[116:119], v[202:205], v[104:107]
	v_mfma_f32_16x16x32_bf16 v[72:75], v[124:127], v[202:205], v[72:75]
	v_mfma_f32_16x16x32_bf16 v[136:139], v[120:123], v[176:179], v[136:139]
	v_mfma_f32_16x16x32_bf16 v[92:95], v[140:143], v[176:179], v[92:95]
	v_mfma_f32_16x16x32_bf16 v[132:135], v[120:123], v[184:187], v[132:135]
	v_mfma_f32_16x16x32_bf16 v[88:91], v[140:143], v[184:187], v[88:91]
	v_mfma_f32_16x16x32_bf16 v[112:115], v[120:123], v[198:201], v[112:115]
	v_mfma_f32_16x16x32_bf16 v[80:83], v[140:143], v[198:201], v[80:83]
	v_mfma_f32_16x16x32_bf16 v[104:107], v[120:123], v[212:215], v[104:107]
	v_mfma_f32_16x16x32_bf16 v[72:75], v[140:143], v[212:215], v[72:75]
	v_mfma_f32_16x16x32_bf16 v[128:131], v[144:147], v[170:173], v[128:131]
	v_mfma_f32_16x16x32_bf16 v[84:87], v[152:155], v[170:173], v[84:87]
	v_mfma_f32_16x16x32_bf16 v[108:111], v[144:147], v[180:183], v[108:111]
	v_mfma_f32_16x16x32_bf16 v[76:79], v[152:155], v[180:183], v[76:79]
	v_mfma_f32_16x16x32_bf16 v[100:103], v[144:147], v[194:197], v[100:103]
	v_mfma_f32_16x16x32_bf16 v[68:71], v[152:155], v[194:197], v[68:71]
	v_mfma_f32_16x16x32_bf16 v[96:99], v[144:147], v[202:205], v[96:99]
	v_mfma_f32_16x16x32_bf16 v[64:67], v[152:155], v[202:205], v[64:67]
	v_mfma_f32_16x16x32_bf16 v[128:131], v[148:151], v[176:179], v[128:131]
	v_mfma_f32_16x16x32_bf16 v[84:87], v[156:159], v[176:179], v[84:87]
	v_mfma_f32_16x16x32_bf16 v[108:111], v[148:151], v[184:187], v[108:111]
	v_mfma_f32_16x16x32_bf16 v[76:79], v[156:159], v[184:187], v[76:79]
	v_mfma_f32_16x16x32_bf16 v[100:103], v[148:151], v[198:201], v[100:103]
	v_mfma_f32_16x16x32_bf16 v[68:71], v[156:159], v[198:201], v[68:71]
	v_mfma_f32_16x16x32_bf16 v[96:99], v[148:151], v[212:215], v[96:99]
	v_mfma_f32_16x16x32_bf16 v[64:67], v[156:159], v[212:215], v[64:67]
	s_barrier
	s_add_i32 s28, s51, s36
	v_lshl_add_u64 v[188:189], v[188:189], 0, s[74:75]
	s_mov_b32 m0, s28
	ds_read_b128 v[170:173], v193 offset:49152
	ds_read_b128 v[176:179], v193 offset:50176
	ds_read_b128 v[180:183], v193 offset:51200
	ds_read_b128 v[184:187], v193 offset:52224
	ds_read_b128 v[194:197], v193 offset:53248
	ds_read_b128 v[198:201], v193 offset:54272
	ds_read_b128 v[202:205], v193 offset:55296
	ds_read_b128 v[212:215], v193 offset:56320
	global_load_lds_dwordx4 v[188:189], off
	s_add_i32 m0, s28, 0x2000
	s_add_u32 s26, s26, 0x40080
	v_lshl_add_u64 v[188:189], v[216:217], 0, s[74:75]
	s_addc_u32 s27, s27, 0
	s_add_i32 s28, s52, s36
	global_load_lds_dwordx4 v[188:189], off
	v_lshl_add_u64 v[188:189], s[26:27], 0, v[168:169]
	s_mov_b32 m0, s28
	s_nop 0
	global_load_lds_dwordx4 v[188:189], off
	v_lshl_add_u64 v[188:189], s[26:27], 0, v[160:161]
	s_add_i32 m0, s28, 0x2000
	s_nop 0
	global_load_lds_dwordx4 v[188:189], off
	v_lshl_add_u64 v[188:189], v[218:219], 0, s[74:75]
	s_mov_b32 m0, s41
	s_nop 0
	global_load_lds_dwordx4 v[188:189], off
	v_lshl_add_u64 v[188:189], v[220:221], 0, s[74:75]
	s_mov_b32 m0, s42
	s_nop 0
	global_load_lds_dwordx4 v[188:189], off
	s_waitcnt vmcnt(8)
	s_waitcnt lgkmcnt(0)
	s_barrier
	s_waitcnt lgkmcnt(0)
	v_mfma_f32_16x16x32_bf16 v[60:63], v[116:119], v[170:173], v[60:63]
	v_mfma_f32_16x16x32_bf16 v[28:31], v[124:127], v[170:173], v[28:31]
	v_mfma_f32_16x16x32_bf16 v[56:59], v[116:119], v[180:183], v[56:59]
	v_mfma_f32_16x16x32_bf16 v[24:27], v[124:127], v[180:183], v[24:27]
	v_mfma_f32_16x16x32_bf16 v[48:51], v[116:119], v[194:197], v[48:51]
	v_mfma_f32_16x16x32_bf16 v[16:19], v[124:127], v[194:197], v[16:19]
	v_mfma_f32_16x16x32_bf16 v[40:43], v[116:119], v[202:205], v[40:43]
	v_mfma_f32_16x16x32_bf16 v[8:11], v[124:127], v[202:205], v[8:11]
	v_mfma_f32_16x16x32_bf16 v[60:63], v[120:123], v[176:179], v[60:63]
	v_mfma_f32_16x16x32_bf16 v[28:31], v[140:143], v[176:179], v[28:31]
	v_mfma_f32_16x16x32_bf16 v[56:59], v[120:123], v[184:187], v[56:59]
	v_mfma_f32_16x16x32_bf16 v[24:27], v[140:143], v[184:187], v[24:27]
	v_mfma_f32_16x16x32_bf16 v[48:51], v[120:123], v[198:201], v[48:51]
	v_mfma_f32_16x16x32_bf16 v[16:19], v[140:143], v[198:201], v[16:19]
	v_mfma_f32_16x16x32_bf16 v[40:43], v[120:123], v[212:215], v[40:43]
	v_mfma_f32_16x16x32_bf16 v[8:11], v[140:143], v[212:215], v[8:11]
	v_mfma_f32_16x16x32_bf16 v[52:55], v[144:147], v[170:173], v[52:55]
	v_mfma_f32_16x16x32_bf16 v[20:23], v[152:155], v[170:173], v[20:23]
	v_mfma_f32_16x16x32_bf16 v[44:47], v[144:147], v[180:183], v[44:47]
	v_mfma_f32_16x16x32_bf16 v[12:15], v[152:155], v[180:183], v[12:15]
	v_mfma_f32_16x16x32_bf16 v[36:39], v[144:147], v[194:197], v[36:39]
	v_mfma_f32_16x16x32_bf16 v[4:7], v[152:155], v[194:197], v[4:7]
	v_mfma_f32_16x16x32_bf16 v[32:35], v[144:147], v[202:205], v[32:35]
	v_mfma_f32_16x16x32_bf16 v[0:3], v[152:155], v[202:205], v[0:3]
	v_mfma_f32_16x16x32_bf16 v[52:55], v[148:151], v[176:179], v[52:55]
	v_mfma_f32_16x16x32_bf16 v[20:23], v[156:159], v[176:179], v[20:23]
	v_mfma_f32_16x16x32_bf16 v[44:47], v[148:151], v[184:187], v[44:47]
	v_mfma_f32_16x16x32_bf16 v[12:15], v[156:159], v[184:187], v[12:15]
	v_mfma_f32_16x16x32_bf16 v[36:39], v[148:151], v[198:201], v[36:39]
	v_mfma_f32_16x16x32_bf16 v[4:7], v[156:159], v[198:201], v[4:7]
	v_mfma_f32_16x16x32_bf16 v[32:35], v[148:151], v[212:215], v[32:35]
	v_mfma_f32_16x16x32_bf16 v[0:3], v[156:159], v[212:215], v[0:3]
	s_barrier
	s_add_i32 s50, s50, 2
	s_add_u32 s48, s48, 0x100
	s_addc_u32 s49, s49, 0
	s_add_u32 s24, s24, 0x100
	s_addc_u32 s25, s25, 0
	s_cmp_gt_u32 s50, 13
	s_cbranch_scc0 .LBB0_779
	s_and_b64 vcc, exec, s[10:11]
	s_cbranch_vccz .LBB0_782
	s_barrier
.LBB0_782:
	v_lshl_or_b32 v184, s44, 7, v192
	v_ashrrev_i32_e32 v185, 31, v184
	v_lshlrev_b64 v[116:117], 2, v[184:185]
	v_lshl_add_u64 v[182:183], s[0:1], 0, v[116:117]
	v_lshl_add_u64 v[180:181], s[12:13], 0, v[116:117]
	v_lshl_add_u64 v[178:179], s[14:15], 0, v[116:117]
	v_lshl_add_u64 v[176:177], s[2:3], 0, v[116:117]
	global_load_dwordx4 v[140:143], v[182:183], off offset:16
	global_load_dwordx4 v[156:159], v[182:183], off
	global_load_dwordx4 v[116:119], v[180:181], off offset:16
	global_load_dwordx4 v[144:147], v[180:181], off
	global_load_dwordx4 v[120:123], v[178:179], off offset:16
	global_load_dwordx4 v[148:151], v[178:179], off
	global_load_dwordx4 v[124:127], v[176:177], off offset:16
	global_load_dwordx4 v[152:155], v[176:177], off
	v_lshl_add_u32 v194, s45, 8, v190
	s_movk_i32 s17, 0xb00
	v_readlane_b32 s24, v253, 0
	v_readlane_b32 s25, v253, 1
	v_readlane_b32 s26, v253, 2
	v_readlane_b32 s27, v253, 3
	s_andn2_b64 vcc, exec, s[6:7]
	v_mul_lo_u32 v194, v194, s17
	v_mov_b32_e32 v188, 0xbfb8aa3b
	v_mov_b32_e32 v189, 0xbfb8aa3b
	v_add_lshl_u32 v194, v194, v184, 1
	v_mov_b32_dpp v172, v136 row_ror:1 row_mask:0xf bank_mask:0xf
	v_mov_b32_dpp v176, v132 row_ror:1 row_mask:0xf bank_mask:0xf
	v_mov_b32_dpp v178, v112 row_ror:1 row_mask:0xf bank_mask:0xf
	v_mov_b32_dpp v180, v132 row_ror:15 row_mask:0xf bank_mask:0xf
	v_mov_b32_dpp v182, v112 row_ror:15 row_mask:0xf bank_mask:0xf
	v_mov_b32_dpp v184, v104 row_ror:15 row_mask:0xf bank_mask:0xf
	v_mov_b32_dpp v173, v137 row_ror:1 row_mask:0xf bank_mask:0xf
	v_mov_b32_dpp v177, v133 row_ror:1 row_mask:0xf bank_mask:0xf
	v_mov_b32_dpp v179, v113 row_ror:1 row_mask:0xf bank_mask:0xf
	v_mov_b32_dpp v181, v133 row_ror:15 row_mask:0xf bank_mask:0xf
	v_mov_b32_dpp v183, v113 row_ror:15 row_mask:0xf bank_mask:0xf
	v_mov_b32_dpp v185, v105 row_ror:15 row_mask:0xf bank_mask:0xf
	v_mov_b32_dpp v170, v136 row_shr:1 row_mask:0xf bank_mask:0xf bound_ctrl:1
	v_mov_b32_dpp v172, v132 row_shr:1 row_mask:0xf bank_mask:0xf
	v_mov_b32_dpp v176, v112 row_shr:1 row_mask:0xf bank_mask:0xf
	v_mov_b32_dpp v178, v104 row_shr:1 row_mask:0xf bank_mask:0xf
	v_mov_b32_dpp v180, v136 row_shl:1 row_mask:0xf bank_mask:0xf
	v_mov_b32_dpp v182, v132 row_shl:1 row_mask:0xf bank_mask:0xf
	v_mov_b32_dpp v184, v112 row_shl:1 row_mask:0xf bank_mask:0xf
	v_mov_b32_dpp v186, v104 row_shl:1 row_mask:0xf bank_mask:0xf bound_ctrl:1
	v_mov_b32_dpp v171, v137 row_shr:1 row_mask:0xf bank_mask:0xf bound_ctrl:1
	v_mov_b32_dpp v173, v133 row_shr:1 row_mask:0xf bank_mask:0xf
	v_mov_b32_dpp v177, v113 row_shr:1 row_mask:0xf bank_mask:0xf
	v_mov_b32_dpp v179, v105 row_shr:1 row_mask:0xf bank_mask:0xf
	v_mov_b32_dpp v181, v137 row_shl:1 row_mask:0xf bank_mask:0xf
	v_mov_b32_dpp v183, v133 row_shl:1 row_mask:0xf bank_mask:0xf
	v_mov_b32_dpp v185, v113 row_shl:1 row_mask:0xf bank_mask:0xf
	v_mov_b32_dpp v187, v105 row_shl:1 row_mask:0xf bank_mask:0xf bound_ctrl:1
	s_waitcnt vmcnt(0)
	v_pk_fma_f32 v[170:171], v[170:171], v[156:157], v[152:153]
	v_pk_fma_f32 v[172:173], v[172:173], v[156:157], v[152:153]
	v_pk_fma_f32 v[176:177], v[176:177], v[156:157], v[152:153]
	v_pk_fma_f32 v[178:179], v[178:179], v[156:157], v[152:153]
	v_pk_fma_f32 v[170:171], v[136:137], v[144:145], v[170:171]
	v_pk_fma_f32 v[172:173], v[132:133], v[144:145], v[172:173]
	v_pk_fma_f32 v[176:177], v[112:113], v[144:145], v[176:177]
	v_pk_fma_f32 v[178:179], v[104:105], v[144:145], v[178:179]
	v_pk_fma_f32 v[170:171], v[180:181], v[148:149], v[170:171]
	v_pk_fma_f32 v[172:173], v[182:183], v[148:149], v[172:173]
	v_pk_fma_f32 v[176:177], v[184:185], v[148:149], v[176:177]
	v_pk_fma_f32 v[178:179], v[186:187], v[148:149], v[178:179]
	v_pk_mul_f32 v[180:181], v[170:171], v[188:189]
	v_pk_mul_f32 v[182:183], v[172:173], v[188:189]
	v_pk_mul_f32 v[184:185], v[176:177], v[188:189]
	v_pk_mul_f32 v[186:187], v[178:179], v[188:189]
	v_exp_f32_e32 v180, v180
	v_exp_f32_e32 v181, v181
	v_exp_f32_e32 v182, v182
	v_exp_f32_e32 v183, v183
	v_exp_f32_e32 v184, v184
	v_exp_f32_e32 v185, v185
	v_exp_f32_e32 v186, v186
	v_exp_f32_e32 v187, v187
	s_nop 0
	v_pk_add_f32 v[180:181], v[180:181], 1.0 op_sel_hi:[1,0]
	v_pk_add_f32 v[182:183], v[182:183], 1.0 op_sel_hi:[1,0]
	v_pk_add_f32 v[184:185], v[184:185], 1.0 op_sel_hi:[1,0]
	v_pk_add_f32 v[186:187], v[186:187], 1.0 op_sel_hi:[1,0]
	v_rcp_f32_e32 v180, v180
	v_rcp_f32_e32 v181, v181
	v_rcp_f32_e32 v182, v182
	v_rcp_f32_e32 v183, v183
	v_rcp_f32_e32 v184, v184
	v_rcp_f32_e32 v185, v185
	v_rcp_f32_e32 v186, v186
	v_rcp_f32_e32 v187, v187
	s_nop 0
	v_pk_mul_f32 v[136:137], v[170:171], v[180:181]
	v_pk_mul_f32 v[132:133], v[172:173], v[182:183]
	v_pk_mul_f32 v[112:113], v[176:177], v[184:185]
	v_pk_mul_f32 v[104:105], v[178:179], v[186:187]
	v_pk_mul_f32 v[136:137], v[136:137], v[128:129]
	v_pk_mul_f32 v[132:133], v[132:133], v[108:109]
	v_pk_mul_f32 v[112:113], v[112:113], v[100:101]
	v_pk_mul_f32 v[104:105], v[104:105], v[96:97]
	v_mov_b32_dpp v172, v138 row_ror:1 row_mask:0xf bank_mask:0xf
	v_mov_b32_dpp v176, v134 row_ror:1 row_mask:0xf bank_mask:0xf
	v_mov_b32_dpp v178, v114 row_ror:1 row_mask:0xf bank_mask:0xf
	v_mov_b32_dpp v180, v134 row_ror:15 row_mask:0xf bank_mask:0xf
	v_mov_b32_dpp v182, v114 row_ror:15 row_mask:0xf bank_mask:0xf
	v_mov_b32_dpp v184, v106 row_ror:15 row_mask:0xf bank_mask:0xf
	v_mov_b32_dpp v173, v139 row_ror:1 row_mask:0xf bank_mask:0xf
	v_mov_b32_dpp v177, v135 row_ror:1 row_mask:0xf bank_mask:0xf
	v_mov_b32_dpp v179, v115 row_ror:1 row_mask:0xf bank_mask:0xf
	v_mov_b32_dpp v181, v135 row_ror:15 row_mask:0xf bank_mask:0xf
	v_mov_b32_dpp v183, v115 row_ror:15 row_mask:0xf bank_mask:0xf
	v_mov_b32_dpp v185, v107 row_ror:15 row_mask:0xf bank_mask:0xf
	v_mov_b32_dpp v170, v138 row_shr:1 row_mask:0xf bank_mask:0xf bound_ctrl:1
	v_mov_b32_dpp v172, v134 row_shr:1 row_mask:0xf bank_mask:0xf
	v_mov_b32_dpp v176, v114 row_shr:1 row_mask:0xf bank_mask:0xf
	v_mov_b32_dpp v178, v106 row_shr:1 row_mask:0xf bank_mask:0xf
	v_mov_b32_dpp v180, v138 row_shl:1 row_mask:0xf bank_mask:0xf
	v_mov_b32_dpp v182, v134 row_shl:1 row_mask:0xf bank_mask:0xf
	v_mov_b32_dpp v184, v114 row_shl:1 row_mask:0xf bank_mask:0xf
	v_mov_b32_dpp v186, v106 row_shl:1 row_mask:0xf bank_mask:0xf bound_ctrl:1
	v_mov_b32_dpp v171, v139 row_shr:1 row_mask:0xf bank_mask:0xf bound_ctrl:1
	v_mov_b32_dpp v173, v135 row_shr:1 row_mask:0xf bank_mask:0xf
	v_mov_b32_dpp v177, v115 row_shr:1 row_mask:0xf bank_mask:0xf
	v_mov_b32_dpp v179, v107 row_shr:1 row_mask:0xf bank_mask:0xf
	v_mov_b32_dpp v181, v139 row_shl:1 row_mask:0xf bank_mask:0xf
	v_mov_b32_dpp v183, v135 row_shl:1 row_mask:0xf bank_mask:0xf
	v_mov_b32_dpp v185, v115 row_shl:1 row_mask:0xf bank_mask:0xf
	v_mov_b32_dpp v187, v107 row_shl:1 row_mask:0xf bank_mask:0xf bound_ctrl:1
	v_pk_fma_f32 v[170:171], v[170:171], v[158:159], v[154:155]
	v_pk_fma_f32 v[172:173], v[172:173], v[158:159], v[154:155]
	v_pk_fma_f32 v[176:177], v[176:177], v[158:159], v[154:155]
	v_pk_fma_f32 v[178:179], v[178:179], v[158:159], v[154:155]
	v_pk_fma_f32 v[170:171], v[138:139], v[146:147], v[170:171]
	v_pk_fma_f32 v[172:173], v[134:135], v[146:147], v[172:173]
	v_pk_fma_f32 v[176:177], v[114:115], v[146:147], v[176:177]
	v_pk_fma_f32 v[178:179], v[106:107], v[146:147], v[178:179]
	v_pk_fma_f32 v[170:171], v[180:181], v[150:151], v[170:171]
	v_pk_fma_f32 v[172:173], v[182:183], v[150:151], v[172:173]
	v_pk_fma_f32 v[176:177], v[184:185], v[150:151], v[176:177]
	v_pk_fma_f32 v[178:179], v[186:187], v[150:151], v[178:179]
	v_pk_mul_f32 v[180:181], v[170:171], v[188:189]
	v_pk_mul_f32 v[182:183], v[172:173], v[188:189]
	v_pk_mul_f32 v[184:185], v[176:177], v[188:189]
	v_pk_mul_f32 v[186:187], v[178:179], v[188:189]
	v_exp_f32_e32 v180, v180
	v_exp_f32_e32 v181, v181
	v_exp_f32_e32 v182, v182
	v_exp_f32_e32 v183, v183
	v_exp_f32_e32 v184, v184
	v_exp_f32_e32 v185, v185
	v_exp_f32_e32 v186, v186
	v_exp_f32_e32 v187, v187
	s_nop 0
	v_pk_add_f32 v[180:181], v[180:181], 1.0 op_sel_hi:[1,0]
	v_pk_add_f32 v[182:183], v[182:183], 1.0 op_sel_hi:[1,0]
	v_pk_add_f32 v[184:185], v[184:185], 1.0 op_sel_hi:[1,0]
	v_pk_add_f32 v[186:187], v[186:187], 1.0 op_sel_hi:[1,0]
	v_rcp_f32_e32 v180, v180
	v_rcp_f32_e32 v181, v181
	v_rcp_f32_e32 v182, v182
	v_rcp_f32_e32 v183, v183
	v_rcp_f32_e32 v184, v184
	v_rcp_f32_e32 v185, v185
	v_rcp_f32_e32 v186, v186
	v_rcp_f32_e32 v187, v187
	s_nop 0
	v_pk_mul_f32 v[138:139], v[170:171], v[180:181]
	v_pk_mul_f32 v[134:135], v[172:173], v[182:183]
	v_pk_mul_f32 v[114:115], v[176:177], v[184:185]
	v_pk_mul_f32 v[106:107], v[178:179], v[186:187]
	v_pk_mul_f32 v[138:139], v[138:139], v[130:131]
	v_pk_mul_f32 v[134:135], v[134:135], v[110:111]
	v_pk_mul_f32 v[114:115], v[114:115], v[102:103]
	v_pk_mul_f32 v[106:107], v[106:107], v[98:99]
	v_mov_b32_dpp v172, v92 row_ror:1 row_mask:0xf bank_mask:0xf
	v_mov_b32_dpp v176, v88 row_ror:1 row_mask:0xf bank_mask:0xf
	v_mov_b32_dpp v178, v80 row_ror:1 row_mask:0xf bank_mask:0xf
	v_mov_b32_dpp v180, v88 row_ror:15 row_mask:0xf bank_mask:0xf
	v_mov_b32_dpp v182, v80 row_ror:15 row_mask:0xf bank_mask:0xf
	v_mov_b32_dpp v184, v72 row_ror:15 row_mask:0xf bank_mask:0xf
	v_mov_b32_dpp v173, v93 row_ror:1 row_mask:0xf bank_mask:0xf
	v_mov_b32_dpp v177, v89 row_ror:1 row_mask:0xf bank_mask:0xf
	v_mov_b32_dpp v179, v81 row_ror:1 row_mask:0xf bank_mask:0xf
	v_mov_b32_dpp v181, v89 row_ror:15 row_mask:0xf bank_mask:0xf
	v_mov_b32_dpp v183, v81 row_ror:15 row_mask:0xf bank_mask:0xf
	v_mov_b32_dpp v185, v73 row_ror:15 row_mask:0xf bank_mask:0xf
	v_mov_b32_dpp v170, v92 row_shr:1 row_mask:0xf bank_mask:0xf bound_ctrl:1
	v_mov_b32_dpp v172, v88 row_shr:1 row_mask:0xf bank_mask:0xf
	v_mov_b32_dpp v176, v80 row_shr:1 row_mask:0xf bank_mask:0xf
	v_mov_b32_dpp v178, v72 row_shr:1 row_mask:0xf bank_mask:0xf
	v_mov_b32_dpp v180, v92 row_shl:1 row_mask:0xf bank_mask:0xf
	v_mov_b32_dpp v182, v88 row_shl:1 row_mask:0xf bank_mask:0xf
	v_mov_b32_dpp v184, v80 row_shl:1 row_mask:0xf bank_mask:0xf
	v_mov_b32_dpp v186, v72 row_shl:1 row_mask:0xf bank_mask:0xf bound_ctrl:1
	v_mov_b32_dpp v171, v93 row_shr:1 row_mask:0xf bank_mask:0xf bound_ctrl:1
	v_mov_b32_dpp v173, v89 row_shr:1 row_mask:0xf bank_mask:0xf
	v_mov_b32_dpp v177, v81 row_shr:1 row_mask:0xf bank_mask:0xf
	v_mov_b32_dpp v179, v73 row_shr:1 row_mask:0xf bank_mask:0xf
	v_mov_b32_dpp v181, v93 row_shl:1 row_mask:0xf bank_mask:0xf
	v_mov_b32_dpp v183, v89 row_shl:1 row_mask:0xf bank_mask:0xf
	v_mov_b32_dpp v185, v81 row_shl:1 row_mask:0xf bank_mask:0xf
	v_mov_b32_dpp v187, v73 row_shl:1 row_mask:0xf bank_mask:0xf bound_ctrl:1
	v_pk_fma_f32 v[170:171], v[170:171], v[140:141], v[124:125]
	v_pk_fma_f32 v[172:173], v[172:173], v[140:141], v[124:125]
	v_pk_fma_f32 v[176:177], v[176:177], v[140:141], v[124:125]
	v_pk_fma_f32 v[178:179], v[178:179], v[140:141], v[124:125]
	v_pk_fma_f32 v[170:171], v[92:93], v[116:117], v[170:171]
	v_pk_fma_f32 v[172:173], v[88:89], v[116:117], v[172:173]
	v_pk_fma_f32 v[176:177], v[80:81], v[116:117], v[176:177]
	v_pk_fma_f32 v[178:179], v[72:73], v[116:117], v[178:179]
	v_pk_fma_f32 v[170:171], v[180:181], v[120:121], v[170:171]
	v_pk_fma_f32 v[172:173], v[182:183], v[120:121], v[172:173]
	v_pk_fma_f32 v[176:177], v[184:185], v[120:121], v[176:177]
	v_pk_fma_f32 v[178:179], v[186:187], v[120:121], v[178:179]
	v_pk_mul_f32 v[180:181], v[170:171], v[188:189]
	v_pk_mul_f32 v[182:183], v[172:173], v[188:189]
	v_pk_mul_f32 v[184:185], v[176:177], v[188:189]
	v_pk_mul_f32 v[186:187], v[178:179], v[188:189]
	v_exp_f32_e32 v180, v180
	v_exp_f32_e32 v181, v181
	v_exp_f32_e32 v182, v182
	v_exp_f32_e32 v183, v183
	v_exp_f32_e32 v184, v184
	v_exp_f32_e32 v185, v185
	v_exp_f32_e32 v186, v186
	v_exp_f32_e32 v187, v187
	s_nop 0
	v_pk_add_f32 v[180:181], v[180:181], 1.0 op_sel_hi:[1,0]
	v_pk_add_f32 v[182:183], v[182:183], 1.0 op_sel_hi:[1,0]
	v_pk_add_f32 v[184:185], v[184:185], 1.0 op_sel_hi:[1,0]
	v_pk_add_f32 v[186:187], v[186:187], 1.0 op_sel_hi:[1,0]
	v_rcp_f32_e32 v180, v180
	v_rcp_f32_e32 v181, v181
	v_rcp_f32_e32 v182, v182
	v_rcp_f32_e32 v183, v183
	v_rcp_f32_e32 v184, v184
	v_rcp_f32_e32 v185, v185
	v_rcp_f32_e32 v186, v186
	v_rcp_f32_e32 v187, v187
	s_nop 0
	v_pk_mul_f32 v[92:93], v[170:171], v[180:181]
	v_pk_mul_f32 v[88:89], v[172:173], v[182:183]
	v_pk_mul_f32 v[80:81], v[176:177], v[184:185]
	v_pk_mul_f32 v[72:73], v[178:179], v[186:187]
	v_pk_mul_f32 v[92:93], v[92:93], v[84:85]
	v_pk_mul_f32 v[88:89], v[88:89], v[76:77]
	v_pk_mul_f32 v[80:81], v[80:81], v[68:69]
	v_pk_mul_f32 v[72:73], v[72:73], v[64:65]
	v_mov_b32_dpp v172, v94 row_ror:1 row_mask:0xf bank_mask:0xf
	v_mov_b32_dpp v176, v90 row_ror:1 row_mask:0xf bank_mask:0xf
	v_mov_b32_dpp v178, v82 row_ror:1 row_mask:0xf bank_mask:0xf
	v_mov_b32_dpp v180, v90 row_ror:15 row_mask:0xf bank_mask:0xf
	v_mov_b32_dpp v182, v82 row_ror:15 row_mask:0xf bank_mask:0xf
	v_mov_b32_dpp v184, v74 row_ror:15 row_mask:0xf bank_mask:0xf
	v_mov_b32_dpp v173, v95 row_ror:1 row_mask:0xf bank_mask:0xf
	v_mov_b32_dpp v177, v91 row_ror:1 row_mask:0xf bank_mask:0xf
	v_mov_b32_dpp v179, v83 row_ror:1 row_mask:0xf bank_mask:0xf
	v_mov_b32_dpp v181, v91 row_ror:15 row_mask:0xf bank_mask:0xf
	v_mov_b32_dpp v183, v83 row_ror:15 row_mask:0xf bank_mask:0xf
	v_mov_b32_dpp v185, v75 row_ror:15 row_mask:0xf bank_mask:0xf
	v_mov_b32_dpp v170, v94 row_shr:1 row_mask:0xf bank_mask:0xf bound_ctrl:1
	v_mov_b32_dpp v172, v90 row_shr:1 row_mask:0xf bank_mask:0xf
	v_mov_b32_dpp v176, v82 row_shr:1 row_mask:0xf bank_mask:0xf
	v_mov_b32_dpp v178, v74 row_shr:1 row_mask:0xf bank_mask:0xf
	v_mov_b32_dpp v180, v94 row_shl:1 row_mask:0xf bank_mask:0xf
	v_mov_b32_dpp v182, v90 row_shl:1 row_mask:0xf bank_mask:0xf
	v_mov_b32_dpp v184, v82 row_shl:1 row_mask:0xf bank_mask:0xf
	v_mov_b32_dpp v186, v74 row_shl:1 row_mask:0xf bank_mask:0xf bound_ctrl:1
	v_mov_b32_dpp v171, v95 row_shr:1 row_mask:0xf bank_mask:0xf bound_ctrl:1
	v_mov_b32_dpp v173, v91 row_shr:1 row_mask:0xf bank_mask:0xf
	v_mov_b32_dpp v177, v83 row_shr:1 row_mask:0xf bank_mask:0xf
	v_mov_b32_dpp v179, v75 row_shr:1 row_mask:0xf bank_mask:0xf
	v_mov_b32_dpp v181, v95 row_shl:1 row_mask:0xf bank_mask:0xf
	v_mov_b32_dpp v183, v91 row_shl:1 row_mask:0xf bank_mask:0xf
	v_mov_b32_dpp v185, v83 row_shl:1 row_mask:0xf bank_mask:0xf
	v_mov_b32_dpp v187, v75 row_shl:1 row_mask:0xf bank_mask:0xf bound_ctrl:1
	v_pk_fma_f32 v[170:171], v[170:171], v[142:143], v[126:127]
	v_pk_fma_f32 v[172:173], v[172:173], v[142:143], v[126:127]
	v_pk_fma_f32 v[176:177], v[176:177], v[142:143], v[126:127]
	v_pk_fma_f32 v[178:179], v[178:179], v[142:143], v[126:127]
	v_pk_fma_f32 v[170:171], v[94:95], v[118:119], v[170:171]
	v_pk_fma_f32 v[172:173], v[90:91], v[118:119], v[172:173]
	v_pk_fma_f32 v[176:177], v[82:83], v[118:119], v[176:177]
	v_pk_fma_f32 v[178:179], v[74:75], v[118:119], v[178:179]
	v_pk_fma_f32 v[170:171], v[180:181], v[122:123], v[170:171]
	v_pk_fma_f32 v[172:173], v[182:183], v[122:123], v[172:173]
	v_pk_fma_f32 v[176:177], v[184:185], v[122:123], v[176:177]
	v_pk_fma_f32 v[178:179], v[186:187], v[122:123], v[178:179]
	v_pk_mul_f32 v[180:181], v[170:171], v[188:189]
	v_pk_mul_f32 v[182:183], v[172:173], v[188:189]
	v_pk_mul_f32 v[184:185], v[176:177], v[188:189]
	v_pk_mul_f32 v[186:187], v[178:179], v[188:189]
	v_exp_f32_e32 v180, v180
	v_exp_f32_e32 v181, v181
	v_exp_f32_e32 v182, v182
	v_exp_f32_e32 v183, v183
	v_exp_f32_e32 v184, v184
	v_exp_f32_e32 v185, v185
	v_exp_f32_e32 v186, v186
	v_exp_f32_e32 v187, v187
	s_nop 0
	v_pk_add_f32 v[180:181], v[180:181], 1.0 op_sel_hi:[1,0]
	v_pk_add_f32 v[182:183], v[182:183], 1.0 op_sel_hi:[1,0]
	v_pk_add_f32 v[184:185], v[184:185], 1.0 op_sel_hi:[1,0]
	v_pk_add_f32 v[186:187], v[186:187], 1.0 op_sel_hi:[1,0]
	v_rcp_f32_e32 v180, v180
	v_rcp_f32_e32 v181, v181
	v_rcp_f32_e32 v182, v182
	v_rcp_f32_e32 v183, v183
	v_rcp_f32_e32 v184, v184
	v_rcp_f32_e32 v185, v185
	v_rcp_f32_e32 v186, v186
	v_rcp_f32_e32 v187, v187
	s_nop 0
	v_pk_mul_f32 v[94:95], v[170:171], v[180:181]
	v_pk_mul_f32 v[90:91], v[172:173], v[182:183]
	v_pk_mul_f32 v[82:83], v[176:177], v[184:185]
	v_pk_mul_f32 v[74:75], v[178:179], v[186:187]
	v_pk_mul_f32 v[94:95], v[94:95], v[86:87]
	v_pk_mul_f32 v[90:91], v[90:91], v[78:79]
	v_pk_mul_f32 v[82:83], v[82:83], v[70:71]
	v_pk_mul_f32 v[74:75], v[74:75], v[66:67]
	v_cvt_pk_bf16_f32 v128, v136, v137
	v_cvt_pk_bf16_f32 v129, v138, v139
	v_cvt_pk_bf16_f32 v130, v92, v93
	v_cvt_pk_bf16_f32 v131, v94, v95
	buffer_store_dwordx4 v[128:131], v194, s[24:27], 0 offen sc1
	v_cvt_pk_bf16_f32 v108, v132, v133
	v_cvt_pk_bf16_f32 v109, v134, v135
	v_cvt_pk_bf16_f32 v110, v88, v89
	v_cvt_pk_bf16_f32 v111, v90, v91
	v_add_u32_e32 v195, 0x16000, v194
	buffer_store_dwordx4 v[108:111], v195, s[24:27], 0 offen sc1
	v_cvt_pk_bf16_f32 v100, v112, v113
	v_cvt_pk_bf16_f32 v101, v114, v115
	v_cvt_pk_bf16_f32 v102, v80, v81
	v_cvt_pk_bf16_f32 v103, v82, v83
	v_add_u32_e32 v195, 0x2c000, v194
	buffer_store_dwordx4 v[100:103], v195, s[24:27], 0 offen sc1
	v_cvt_pk_bf16_f32 v96, v104, v105
	v_cvt_pk_bf16_f32 v97, v106, v107
	v_cvt_pk_bf16_f32 v98, v72, v73
	v_cvt_pk_bf16_f32 v99, v74, v75
	v_add_u32_e32 v195, 0x42000, v194
	buffer_store_dwordx4 v[96:99], v195, s[24:27], 0 offen sc1
	v_mov_b32_dpp v172, v60 row_ror:1 row_mask:0xf bank_mask:0xf
	v_mov_b32_dpp v176, v56 row_ror:1 row_mask:0xf bank_mask:0xf
	v_mov_b32_dpp v178, v48 row_ror:1 row_mask:0xf bank_mask:0xf
	v_mov_b32_dpp v180, v56 row_ror:15 row_mask:0xf bank_mask:0xf
	v_mov_b32_dpp v182, v48 row_ror:15 row_mask:0xf bank_mask:0xf
	v_mov_b32_dpp v184, v40 row_ror:15 row_mask:0xf bank_mask:0xf
	v_mov_b32_dpp v173, v61 row_ror:1 row_mask:0xf bank_mask:0xf
	v_mov_b32_dpp v177, v57 row_ror:1 row_mask:0xf bank_mask:0xf
	v_mov_b32_dpp v179, v49 row_ror:1 row_mask:0xf bank_mask:0xf
	v_mov_b32_dpp v181, v57 row_ror:15 row_mask:0xf bank_mask:0xf
	v_mov_b32_dpp v183, v49 row_ror:15 row_mask:0xf bank_mask:0xf
	v_mov_b32_dpp v185, v41 row_ror:15 row_mask:0xf bank_mask:0xf
	v_mov_b32_dpp v170, v60 row_shr:1 row_mask:0xf bank_mask:0xf bound_ctrl:1
	v_mov_b32_dpp v172, v56 row_shr:1 row_mask:0xf bank_mask:0xf
	v_mov_b32_dpp v176, v48 row_shr:1 row_mask:0xf bank_mask:0xf
	v_mov_b32_dpp v178, v40 row_shr:1 row_mask:0xf bank_mask:0xf
	v_mov_b32_dpp v180, v60 row_shl:1 row_mask:0xf bank_mask:0xf
	v_mov_b32_dpp v182, v56 row_shl:1 row_mask:0xf bank_mask:0xf
	v_mov_b32_dpp v184, v48 row_shl:1 row_mask:0xf bank_mask:0xf
	v_mov_b32_dpp v186, v40 row_shl:1 row_mask:0xf bank_mask:0xf bound_ctrl:1
	v_mov_b32_dpp v171, v61 row_shr:1 row_mask:0xf bank_mask:0xf bound_ctrl:1
	v_mov_b32_dpp v173, v57 row_shr:1 row_mask:0xf bank_mask:0xf
	v_mov_b32_dpp v177, v49 row_shr:1 row_mask:0xf bank_mask:0xf
	v_mov_b32_dpp v179, v41 row_shr:1 row_mask:0xf bank_mask:0xf
	v_mov_b32_dpp v181, v61 row_shl:1 row_mask:0xf bank_mask:0xf
	v_mov_b32_dpp v183, v57 row_shl:1 row_mask:0xf bank_mask:0xf
	v_mov_b32_dpp v185, v49 row_shl:1 row_mask:0xf bank_mask:0xf
	v_mov_b32_dpp v187, v41 row_shl:1 row_mask:0xf bank_mask:0xf bound_ctrl:1
	v_pk_fma_f32 v[170:171], v[170:171], v[156:157], v[152:153]
	v_pk_fma_f32 v[172:173], v[172:173], v[156:157], v[152:153]
	v_pk_fma_f32 v[176:177], v[176:177], v[156:157], v[152:153]
	v_pk_fma_f32 v[178:179], v[178:179], v[156:157], v[152:153]
	v_pk_fma_f32 v[170:171], v[60:61], v[144:145], v[170:171]
	v_pk_fma_f32 v[172:173], v[56:57], v[144:145], v[172:173]
	v_pk_fma_f32 v[176:177], v[48:49], v[144:145], v[176:177]
	v_pk_fma_f32 v[178:179], v[40:41], v[144:145], v[178:179]
	v_pk_fma_f32 v[170:171], v[180:181], v[148:149], v[170:171]
	v_pk_fma_f32 v[172:173], v[182:183], v[148:149], v[172:173]
	v_pk_fma_f32 v[176:177], v[184:185], v[148:149], v[176:177]
	v_pk_fma_f32 v[178:179], v[186:187], v[148:149], v[178:179]
	v_pk_mul_f32 v[180:181], v[170:171], v[188:189]
	v_pk_mul_f32 v[182:183], v[172:173], v[188:189]
	v_pk_mul_f32 v[184:185], v[176:177], v[188:189]
	v_pk_mul_f32 v[186:187], v[178:179], v[188:189]
	v_exp_f32_e32 v180, v180
	v_exp_f32_e32 v181, v181
	v_exp_f32_e32 v182, v182
	v_exp_f32_e32 v183, v183
	v_exp_f32_e32 v184, v184
	v_exp_f32_e32 v185, v185
	v_exp_f32_e32 v186, v186
	v_exp_f32_e32 v187, v187
	s_nop 0
	v_pk_add_f32 v[180:181], v[180:181], 1.0 op_sel_hi:[1,0]
	v_pk_add_f32 v[182:183], v[182:183], 1.0 op_sel_hi:[1,0]
	v_pk_add_f32 v[184:185], v[184:185], 1.0 op_sel_hi:[1,0]
	v_pk_add_f32 v[186:187], v[186:187], 1.0 op_sel_hi:[1,0]
	v_rcp_f32_e32 v180, v180
	v_rcp_f32_e32 v181, v181
	v_rcp_f32_e32 v182, v182
	v_rcp_f32_e32 v183, v183
	v_rcp_f32_e32 v184, v184
	v_rcp_f32_e32 v185, v185
	v_rcp_f32_e32 v186, v186
	v_rcp_f32_e32 v187, v187
	s_nop 0
	v_pk_mul_f32 v[60:61], v[170:171], v[180:181]
	v_pk_mul_f32 v[56:57], v[172:173], v[182:183]
	v_pk_mul_f32 v[48:49], v[176:177], v[184:185]
	v_pk_mul_f32 v[40:41], v[178:179], v[186:187]
	v_pk_mul_f32 v[60:61], v[60:61], v[52:53]
	v_pk_mul_f32 v[56:57], v[56:57], v[44:45]
	v_pk_mul_f32 v[48:49], v[48:49], v[36:37]
	v_pk_mul_f32 v[40:41], v[40:41], v[32:33]
	v_mov_b32_dpp v172, v62 row_ror:1 row_mask:0xf bank_mask:0xf
	v_mov_b32_dpp v176, v58 row_ror:1 row_mask:0xf bank_mask:0xf
	v_mov_b32_dpp v178, v50 row_ror:1 row_mask:0xf bank_mask:0xf
	v_mov_b32_dpp v180, v58 row_ror:15 row_mask:0xf bank_mask:0xf
	v_mov_b32_dpp v182, v50 row_ror:15 row_mask:0xf bank_mask:0xf
	v_mov_b32_dpp v184, v42 row_ror:15 row_mask:0xf bank_mask:0xf
	v_mov_b32_dpp v173, v63 row_ror:1 row_mask:0xf bank_mask:0xf
	v_mov_b32_dpp v177, v59 row_ror:1 row_mask:0xf bank_mask:0xf
	v_mov_b32_dpp v179, v51 row_ror:1 row_mask:0xf bank_mask:0xf
	v_mov_b32_dpp v181, v59 row_ror:15 row_mask:0xf bank_mask:0xf
	v_mov_b32_dpp v183, v51 row_ror:15 row_mask:0xf bank_mask:0xf
	v_mov_b32_dpp v185, v43 row_ror:15 row_mask:0xf bank_mask:0xf
	v_mov_b32_dpp v170, v62 row_shr:1 row_mask:0xf bank_mask:0xf bound_ctrl:1
	v_mov_b32_dpp v172, v58 row_shr:1 row_mask:0xf bank_mask:0xf
	v_mov_b32_dpp v176, v50 row_shr:1 row_mask:0xf bank_mask:0xf
	v_mov_b32_dpp v178, v42 row_shr:1 row_mask:0xf bank_mask:0xf
	v_mov_b32_dpp v180, v62 row_shl:1 row_mask:0xf bank_mask:0xf
	v_mov_b32_dpp v182, v58 row_shl:1 row_mask:0xf bank_mask:0xf
	v_mov_b32_dpp v184, v50 row_shl:1 row_mask:0xf bank_mask:0xf
	v_mov_b32_dpp v186, v42 row_shl:1 row_mask:0xf bank_mask:0xf bound_ctrl:1
	v_mov_b32_dpp v171, v63 row_shr:1 row_mask:0xf bank_mask:0xf bound_ctrl:1
	v_mov_b32_dpp v173, v59 row_shr:1 row_mask:0xf bank_mask:0xf
	v_mov_b32_dpp v177, v51 row_shr:1 row_mask:0xf bank_mask:0xf
	v_mov_b32_dpp v179, v43 row_shr:1 row_mask:0xf bank_mask:0xf
	v_mov_b32_dpp v181, v63 row_shl:1 row_mask:0xf bank_mask:0xf
	v_mov_b32_dpp v183, v59 row_shl:1 row_mask:0xf bank_mask:0xf
	v_mov_b32_dpp v185, v51 row_shl:1 row_mask:0xf bank_mask:0xf
	v_mov_b32_dpp v187, v43 row_shl:1 row_mask:0xf bank_mask:0xf bound_ctrl:1
	v_pk_fma_f32 v[170:171], v[170:171], v[158:159], v[154:155]
	v_pk_fma_f32 v[172:173], v[172:173], v[158:159], v[154:155]
	v_pk_fma_f32 v[176:177], v[176:177], v[158:159], v[154:155]
	v_pk_fma_f32 v[178:179], v[178:179], v[158:159], v[154:155]
	v_pk_fma_f32 v[170:171], v[62:63], v[146:147], v[170:171]
	v_pk_fma_f32 v[172:173], v[58:59], v[146:147], v[172:173]
	v_pk_fma_f32 v[176:177], v[50:51], v[146:147], v[176:177]
	v_pk_fma_f32 v[178:179], v[42:43], v[146:147], v[178:179]
	v_pk_fma_f32 v[170:171], v[180:181], v[150:151], v[170:171]
	v_pk_fma_f32 v[172:173], v[182:183], v[150:151], v[172:173]
	v_pk_fma_f32 v[176:177], v[184:185], v[150:151], v[176:177]
	v_pk_fma_f32 v[178:179], v[186:187], v[150:151], v[178:179]
	v_pk_mul_f32 v[180:181], v[170:171], v[188:189]
	v_pk_mul_f32 v[182:183], v[172:173], v[188:189]
	v_pk_mul_f32 v[184:185], v[176:177], v[188:189]
	v_pk_mul_f32 v[186:187], v[178:179], v[188:189]
	v_exp_f32_e32 v180, v180
	v_exp_f32_e32 v181, v181
	v_exp_f32_e32 v182, v182
	v_exp_f32_e32 v183, v183
	v_exp_f32_e32 v184, v184
	v_exp_f32_e32 v185, v185
	v_exp_f32_e32 v186, v186
	v_exp_f32_e32 v187, v187
	s_nop 0
	v_pk_add_f32 v[180:181], v[180:181], 1.0 op_sel_hi:[1,0]
	v_pk_add_f32 v[182:183], v[182:183], 1.0 op_sel_hi:[1,0]
	v_pk_add_f32 v[184:185], v[184:185], 1.0 op_sel_hi:[1,0]
	v_pk_add_f32 v[186:187], v[186:187], 1.0 op_sel_hi:[1,0]
	v_rcp_f32_e32 v180, v180
	v_rcp_f32_e32 v181, v181
	v_rcp_f32_e32 v182, v182
	v_rcp_f32_e32 v183, v183
	v_rcp_f32_e32 v184, v184
	v_rcp_f32_e32 v185, v185
	v_rcp_f32_e32 v186, v186
	v_rcp_f32_e32 v187, v187
	s_nop 0
	v_pk_mul_f32 v[62:63], v[170:171], v[180:181]
	v_pk_mul_f32 v[58:59], v[172:173], v[182:183]
	v_pk_mul_f32 v[50:51], v[176:177], v[184:185]
	v_pk_mul_f32 v[42:43], v[178:179], v[186:187]
	v_pk_mul_f32 v[62:63], v[62:63], v[54:55]
	v_pk_mul_f32 v[58:59], v[58:59], v[46:47]
	v_pk_mul_f32 v[50:51], v[50:51], v[38:39]
	v_pk_mul_f32 v[42:43], v[42:43], v[34:35]
	v_mov_b32_dpp v172, v28 row_ror:1 row_mask:0xf bank_mask:0xf
	v_mov_b32_dpp v176, v24 row_ror:1 row_mask:0xf bank_mask:0xf
	v_mov_b32_dpp v178, v16 row_ror:1 row_mask:0xf bank_mask:0xf
	v_mov_b32_dpp v180, v24 row_ror:15 row_mask:0xf bank_mask:0xf
	v_mov_b32_dpp v182, v16 row_ror:15 row_mask:0xf bank_mask:0xf
	v_mov_b32_dpp v184, v8 row_ror:15 row_mask:0xf bank_mask:0xf
	v_mov_b32_dpp v173, v29 row_ror:1 row_mask:0xf bank_mask:0xf
	v_mov_b32_dpp v177, v25 row_ror:1 row_mask:0xf bank_mask:0xf
	v_mov_b32_dpp v179, v17 row_ror:1 row_mask:0xf bank_mask:0xf
	v_mov_b32_dpp v181, v25 row_ror:15 row_mask:0xf bank_mask:0xf
	v_mov_b32_dpp v183, v17 row_ror:15 row_mask:0xf bank_mask:0xf
	v_mov_b32_dpp v185, v9 row_ror:15 row_mask:0xf bank_mask:0xf
	v_mov_b32_dpp v170, v28 row_shr:1 row_mask:0xf bank_mask:0xf bound_ctrl:1
	v_mov_b32_dpp v172, v24 row_shr:1 row_mask:0xf bank_mask:0xf
	v_mov_b32_dpp v176, v16 row_shr:1 row_mask:0xf bank_mask:0xf
	v_mov_b32_dpp v178, v8 row_shr:1 row_mask:0xf bank_mask:0xf
	v_mov_b32_dpp v180, v28 row_shl:1 row_mask:0xf bank_mask:0xf
	v_mov_b32_dpp v182, v24 row_shl:1 row_mask:0xf bank_mask:0xf
	v_mov_b32_dpp v184, v16 row_shl:1 row_mask:0xf bank_mask:0xf
	v_mov_b32_dpp v186, v8 row_shl:1 row_mask:0xf bank_mask:0xf bound_ctrl:1
	v_mov_b32_dpp v171, v29 row_shr:1 row_mask:0xf bank_mask:0xf bound_ctrl:1
	v_mov_b32_dpp v173, v25 row_shr:1 row_mask:0xf bank_mask:0xf
	v_mov_b32_dpp v177, v17 row_shr:1 row_mask:0xf bank_mask:0xf
	v_mov_b32_dpp v179, v9 row_shr:1 row_mask:0xf bank_mask:0xf
	v_mov_b32_dpp v181, v29 row_shl:1 row_mask:0xf bank_mask:0xf
	v_mov_b32_dpp v183, v25 row_shl:1 row_mask:0xf bank_mask:0xf
	v_mov_b32_dpp v185, v17 row_shl:1 row_mask:0xf bank_mask:0xf
	v_mov_b32_dpp v187, v9 row_shl:1 row_mask:0xf bank_mask:0xf bound_ctrl:1
	v_pk_fma_f32 v[170:171], v[170:171], v[140:141], v[124:125]
	v_pk_fma_f32 v[172:173], v[172:173], v[140:141], v[124:125]
	v_pk_fma_f32 v[176:177], v[176:177], v[140:141], v[124:125]
	v_pk_fma_f32 v[178:179], v[178:179], v[140:141], v[124:125]
	v_pk_fma_f32 v[170:171], v[28:29], v[116:117], v[170:171]
	v_pk_fma_f32 v[172:173], v[24:25], v[116:117], v[172:173]
	v_pk_fma_f32 v[176:177], v[16:17], v[116:117], v[176:177]
	v_pk_fma_f32 v[178:179], v[8:9], v[116:117], v[178:179]
	v_pk_fma_f32 v[170:171], v[180:181], v[120:121], v[170:171]
	v_pk_fma_f32 v[172:173], v[182:183], v[120:121], v[172:173]
	v_pk_fma_f32 v[176:177], v[184:185], v[120:121], v[176:177]
	v_pk_fma_f32 v[178:179], v[186:187], v[120:121], v[178:179]
	v_pk_mul_f32 v[180:181], v[170:171], v[188:189]
	v_pk_mul_f32 v[182:183], v[172:173], v[188:189]
	v_pk_mul_f32 v[184:185], v[176:177], v[188:189]
	v_pk_mul_f32 v[186:187], v[178:179], v[188:189]
	v_exp_f32_e32 v180, v180
	v_exp_f32_e32 v181, v181
	v_exp_f32_e32 v182, v182
	v_exp_f32_e32 v183, v183
	v_exp_f32_e32 v184, v184
	v_exp_f32_e32 v185, v185
	v_exp_f32_e32 v186, v186
	v_exp_f32_e32 v187, v187
	s_nop 0
	v_pk_add_f32 v[180:181], v[180:181], 1.0 op_sel_hi:[1,0]
	v_pk_add_f32 v[182:183], v[182:183], 1.0 op_sel_hi:[1,0]
	v_pk_add_f32 v[184:185], v[184:185], 1.0 op_sel_hi:[1,0]
	v_pk_add_f32 v[186:187], v[186:187], 1.0 op_sel_hi:[1,0]
	v_rcp_f32_e32 v180, v180
	v_rcp_f32_e32 v181, v181
	v_rcp_f32_e32 v182, v182
	v_rcp_f32_e32 v183, v183
	v_rcp_f32_e32 v184, v184
	v_rcp_f32_e32 v185, v185
	v_rcp_f32_e32 v186, v186
	v_rcp_f32_e32 v187, v187
	s_nop 0
	v_pk_mul_f32 v[28:29], v[170:171], v[180:181]
	v_pk_mul_f32 v[24:25], v[172:173], v[182:183]
	v_pk_mul_f32 v[16:17], v[176:177], v[184:185]
	v_pk_mul_f32 v[8:9], v[178:179], v[186:187]
	v_pk_mul_f32 v[28:29], v[28:29], v[20:21]
	v_pk_mul_f32 v[24:25], v[24:25], v[12:13]
	v_pk_mul_f32 v[16:17], v[16:17], v[4:5]
	v_pk_mul_f32 v[8:9], v[8:9], v[0:1]
	v_mov_b32_dpp v172, v30 row_ror:1 row_mask:0xf bank_mask:0xf
	v_mov_b32_dpp v176, v26 row_ror:1 row_mask:0xf bank_mask:0xf
	v_mov_b32_dpp v178, v18 row_ror:1 row_mask:0xf bank_mask:0xf
	v_mov_b32_dpp v180, v26 row_ror:15 row_mask:0xf bank_mask:0xf
	v_mov_b32_dpp v182, v18 row_ror:15 row_mask:0xf bank_mask:0xf
	v_mov_b32_dpp v184, v10 row_ror:15 row_mask:0xf bank_mask:0xf
	v_mov_b32_dpp v173, v31 row_ror:1 row_mask:0xf bank_mask:0xf
	v_mov_b32_dpp v177, v27 row_ror:1 row_mask:0xf bank_mask:0xf
	v_mov_b32_dpp v179, v19 row_ror:1 row_mask:0xf bank_mask:0xf
	v_mov_b32_dpp v181, v27 row_ror:15 row_mask:0xf bank_mask:0xf
	v_mov_b32_dpp v183, v19 row_ror:15 row_mask:0xf bank_mask:0xf
	v_mov_b32_dpp v185, v11 row_ror:15 row_mask:0xf bank_mask:0xf
	v_mov_b32_dpp v170, v30 row_shr:1 row_mask:0xf bank_mask:0xf bound_ctrl:1
	v_mov_b32_dpp v172, v26 row_shr:1 row_mask:0xf bank_mask:0xf
	v_mov_b32_dpp v176, v18 row_shr:1 row_mask:0xf bank_mask:0xf
	v_mov_b32_dpp v178, v10 row_shr:1 row_mask:0xf bank_mask:0xf
	v_mov_b32_dpp v180, v30 row_shl:1 row_mask:0xf bank_mask:0xf
	v_mov_b32_dpp v182, v26 row_shl:1 row_mask:0xf bank_mask:0xf
	v_mov_b32_dpp v184, v18 row_shl:1 row_mask:0xf bank_mask:0xf
	v_mov_b32_dpp v186, v10 row_shl:1 row_mask:0xf bank_mask:0xf bound_ctrl:1
	v_mov_b32_dpp v171, v31 row_shr:1 row_mask:0xf bank_mask:0xf bound_ctrl:1
	v_mov_b32_dpp v173, v27 row_shr:1 row_mask:0xf bank_mask:0xf
	v_mov_b32_dpp v177, v19 row_shr:1 row_mask:0xf bank_mask:0xf
	v_mov_b32_dpp v179, v11 row_shr:1 row_mask:0xf bank_mask:0xf
	v_mov_b32_dpp v181, v31 row_shl:1 row_mask:0xf bank_mask:0xf
	v_mov_b32_dpp v183, v27 row_shl:1 row_mask:0xf bank_mask:0xf
	v_mov_b32_dpp v185, v19 row_shl:1 row_mask:0xf bank_mask:0xf
	v_mov_b32_dpp v187, v11 row_shl:1 row_mask:0xf bank_mask:0xf bound_ctrl:1
	v_pk_fma_f32 v[170:171], v[170:171], v[142:143], v[126:127]
	v_pk_fma_f32 v[172:173], v[172:173], v[142:143], v[126:127]
	v_pk_fma_f32 v[176:177], v[176:177], v[142:143], v[126:127]
	v_pk_fma_f32 v[178:179], v[178:179], v[142:143], v[126:127]
	v_pk_fma_f32 v[170:171], v[30:31], v[118:119], v[170:171]
	v_pk_fma_f32 v[172:173], v[26:27], v[118:119], v[172:173]
	v_pk_fma_f32 v[176:177], v[18:19], v[118:119], v[176:177]
	v_pk_fma_f32 v[178:179], v[10:11], v[118:119], v[178:179]
	v_pk_fma_f32 v[170:171], v[180:181], v[122:123], v[170:171]
	v_pk_fma_f32 v[172:173], v[182:183], v[122:123], v[172:173]
	v_pk_fma_f32 v[176:177], v[184:185], v[122:123], v[176:177]
	v_pk_fma_f32 v[178:179], v[186:187], v[122:123], v[178:179]
	v_pk_mul_f32 v[180:181], v[170:171], v[188:189]
	v_pk_mul_f32 v[182:183], v[172:173], v[188:189]
	v_pk_mul_f32 v[184:185], v[176:177], v[188:189]
	v_pk_mul_f32 v[186:187], v[178:179], v[188:189]
	v_exp_f32_e32 v180, v180
	v_exp_f32_e32 v181, v181
	v_exp_f32_e32 v182, v182
	v_exp_f32_e32 v183, v183
	v_exp_f32_e32 v184, v184
	v_exp_f32_e32 v185, v185
	v_exp_f32_e32 v186, v186
	v_exp_f32_e32 v187, v187
	s_nop 0
	v_pk_add_f32 v[180:181], v[180:181], 1.0 op_sel_hi:[1,0]
	v_pk_add_f32 v[182:183], v[182:183], 1.0 op_sel_hi:[1,0]
	v_pk_add_f32 v[184:185], v[184:185], 1.0 op_sel_hi:[1,0]
	v_pk_add_f32 v[186:187], v[186:187], 1.0 op_sel_hi:[1,0]
	v_rcp_f32_e32 v180, v180
	v_rcp_f32_e32 v181, v181
	v_rcp_f32_e32 v182, v182
	v_rcp_f32_e32 v183, v183
	v_rcp_f32_e32 v184, v184
	v_rcp_f32_e32 v185, v185
	v_rcp_f32_e32 v186, v186
	v_rcp_f32_e32 v187, v187
	s_nop 0
	v_pk_mul_f32 v[30:31], v[170:171], v[180:181]
	v_pk_mul_f32 v[26:27], v[172:173], v[182:183]
	v_pk_mul_f32 v[18:19], v[176:177], v[184:185]
	v_pk_mul_f32 v[10:11], v[178:179], v[186:187]
	v_pk_mul_f32 v[30:31], v[30:31], v[22:23]
	v_pk_mul_f32 v[26:27], v[26:27], v[14:15]
	v_pk_mul_f32 v[18:19], v[18:19], v[6:7]
	v_pk_mul_f32 v[10:11], v[10:11], v[2:3]
	v_cvt_pk_bf16_f32 v52, v60, v61
	v_cvt_pk_bf16_f32 v53, v62, v63
	v_cvt_pk_bf16_f32 v54, v28, v29
	v_cvt_pk_bf16_f32 v55, v30, v31
	v_add_u32_e32 v195, 0xb0000, v194
	buffer_store_dwordx4 v[52:55], v195, s[24:27], 0 offen sc1
	v_cvt_pk_bf16_f32 v44, v56, v57
	v_cvt_pk_bf16_f32 v45, v58, v59
	v_cvt_pk_bf16_f32 v46, v24, v25
	v_cvt_pk_bf16_f32 v47, v26, v27
	v_add_u32_e32 v195, 0xc6000, v194
	buffer_store_dwordx4 v[44:47], v195, s[24:27], 0 offen sc1
	v_cvt_pk_bf16_f32 v36, v48, v49
	v_cvt_pk_bf16_f32 v37, v50, v51
	v_cvt_pk_bf16_f32 v38, v16, v17
	v_cvt_pk_bf16_f32 v39, v18, v19
	v_add_u32_e32 v195, 0xdc000, v194
	buffer_store_dwordx4 v[36:39], v195, s[24:27], 0 offen sc1
	v_cvt_pk_bf16_f32 v32, v40, v41
	v_cvt_pk_bf16_f32 v33, v42, v43
	v_cvt_pk_bf16_f32 v34, v8, v9
	v_cvt_pk_bf16_f32 v35, v10, v11
	v_add_u32_e32 v195, 0xf2000, v194
	buffer_store_dwordx4 v[32:35], v195, s[24:27], 0 offen sc1
	s_mov_b64 s[24:25], -1
	s_cbranch_vccnz .LBB0_775
	s_andn2_b64 vcc, exec, s[8:9]
	s_cbranch_vccnz .LBB0_774
	s_barrier
	s_branch .LBB0_774
